# out-proj fused-norm epilogue (layer 0): f32 residual loads pipelined three row-blocks deep through a register ring instead of load-wait per block
# baseline (speedup 1.0000x reference)
.LBB0_1233:
	v_readlane_b32 s36, v251, 0
	v_readlane_b32 s37, v251, 1
	s_andn2_b64 vcc, exec, s[4:5]
	v_readlane_b32 s38, v251, 2
	v_lshl_add_u64 v[150:151], v[138:139], 2, s[36:37]
	v_readlane_b32 s39, v251, 3
	v_readlane_b32 s40, v251, 4
	v_readlane_b32 s41, v251, 5
	v_readlane_b32 s42, v251, 6
	v_readlane_b32 s43, v251, 7
	v_readlane_b32 s44, v251, 8
	v_readlane_b32 s45, v251, 9
	v_readlane_b32 s46, v251, 10
	v_readlane_b32 s47, v251, 11
	v_readlane_b32 s48, v251, 12
	v_readlane_b32 s49, v251, 13
	v_readlane_b32 s50, v251, 14
	v_readlane_b32 s51, v251, 15
	s_cbranch_vccnz .LBB0_1235
	global_load_dwordx4 v[198:201], v[150:151], off
	global_load_dwordx4 v[202:205], v[150:151], off offset:16
	global_load_dwordx4 v[206:209], v[150:151], off offset:512
	global_load_dwordx4 v[210:213], v[150:151], off offset:528
	s_mov_b32 s98, 0x10000
	s_mov_b32 s99, 0
	v_lshl_add_u64 v[246:247], v[150:151], 0, s[98:99]
	global_load_dwordx4 v[214:217], v[246:247], off
	global_load_dwordx4 v[218:221], v[246:247], off offset:16
	global_load_dwordx4 v[222:225], v[246:247], off offset:512
	global_load_dwordx4 v[226:229], v[246:247], off offset:528
	s_mov_b32 s98, 0x20000
	v_lshl_add_u64 v[246:247], v[150:151], 0, s[98:99]
	global_load_dwordx4 v[230:233], v[246:247], off
	global_load_dwordx4 v[234:237], v[246:247], off offset:16
	global_load_dwordx4 v[238:241], v[246:247], off offset:512
	global_load_dwordx4 v[242:245], v[246:247], off offset:528
	s_waitcnt vmcnt(8)
	v_mov_b64_e32 v[130:131], v[198:199]
	v_mov_b64_e32 v[132:133], v[200:201]
	v_mov_b64_e32 v[134:135], v[202:203]
	v_mov_b64_e32 v[136:137], v[204:205]

.LBB0_1238:
	v_mov_b64_e32 v[138:139], v[206:207]
	v_mov_b64_e32 v[140:141], v[208:209]
	v_mov_b64_e32 v[142:143], v[210:211]
	v_mov_b64_e32 v[144:145], v[212:213]
	s_mov_b32 s98, 0x30000
	s_mov_b32 s99, 0
	v_lshl_add_u64 v[246:247], v[150:151], 0, s[98:99]
	global_load_dwordx4 v[198:201], v[246:247], off
	global_load_dwordx4 v[202:205], v[246:247], off offset:16
	global_load_dwordx4 v[206:209], v[246:247], off offset:512
	global_load_dwordx4 v[210:213], v[246:247], off offset:528
.LBB0_1239:
	s_and_b64 vcc, exec, s[0:1]
	s_cbranch_vccnz .Lopw_0
	s_waitcnt vmcnt(0)
.Lopw_0:
	v_pk_add_f32 v[148:149], v[128:129], v[132:133]
	v_pk_add_f32 v[150:151], v[126:127], v[130:131]
	v_pk_add_f32 v[154:155], v[122:123], v[134:135]
	v_mul_f32_e32 v122, v151, v151
	v_mul_f32_e32 v123, v149, v149
	v_fmac_f32_e32 v122, v150, v150
	v_fmac_f32_e32 v123, v148, v148
	v_pk_add_f32 v[130:131], v[120:121], v[140:141]
	v_pk_add_f32 v[132:133], v[118:119], v[138:139]
	v_pk_add_f32 v[152:153], v[124:125], v[136:137]
	v_add_f32_e32 v122, v122, v123
	v_mul_f32_e32 v123, v155, v155
	v_pk_add_f32 v[136:137], v[114:115], v[142:143]
	v_mul_f32_e32 v114, v133, v133
	v_mul_f32_e32 v115, v131, v131
	v_fmac_f32_e32 v123, v154, v154
	v_fmac_f32_e32 v114, v132, v132
	v_fmac_f32_e32 v115, v130, v130
	v_add_f32_e32 v122, v123, v122
	v_mul_f32_e32 v123, v153, v153
	v_add_f32_e32 v114, v114, v115
	v_mul_f32_e32 v115, v137, v137
	v_fmac_f32_e32 v123, v152, v152
	v_and_b32_e32 v124, 64, v185
	v_pk_add_f32 v[134:135], v[116:117], v[144:145]
	v_fmac_f32_e32 v115, v136, v136
	v_add_f32_e32 v122, v123, v122
	v_xor_b32_e32 v123, 16, v185
	v_add_u32_e32 v124, 64, v124
	v_add_f32_e32 v114, v115, v114
	v_mul_f32_e32 v115, v135, v135
	v_cmp_lt_i32_e32 vcc, v123, v124
	v_fmac_f32_e32 v115, v134, v134
	v_add_f32_e32 v114, v115, v114
	v_cndmask_b32_e32 v123, v185, v123, vcc
	v_lshlrev_b32_e32 v178, 2, v123
	v_add_f32_e32 v114, v122, v114
	ds_bpermute_b32 v115, v178, v114
	v_xor_b32_e32 v116, 32, v185
	v_cmp_lt_i32_e32 vcc, v116, v124
	s_lshl_b32 s12, s25, 2
	s_add_i32 s14, s12, 0
	v_cndmask_b32_e32 v116, v185, v116, vcc
	v_lshlrev_b32_e32 v179, 2, v116
	s_waitcnt lgkmcnt(0)
	v_add_f32_e32 v114, v114, v115
	ds_bpermute_b32 v115, v179, v114
	v_cmp_gt_u32_e64 s[4:5], 16, v173
	s_add_i32 s14, s14, 0x20400
	s_and_saveexec_b64 s[12:13], s[4:5]
	s_cbranch_execz .LBB0_1241
	s_waitcnt lgkmcnt(0)
	v_add_f32_e32 v114, v114, v115
	v_lshl_add_u32 v115, v1, 4, s14
	ds_write_b32 v115, v114

.LBB0_1243:
	v_readlane_b32 s36, v251, 0
	v_readlane_b32 s37, v251, 1
	s_andn2_b64 vcc, exec, s[12:13]
	v_readlane_b32 s38, v251, 2
	v_lshl_add_u64 v[142:143], v[122:123], 2, s[36:37]
	v_readlane_b32 s39, v251, 3
	v_readlane_b32 s40, v251, 4
	v_readlane_b32 s41, v251, 5
	v_readlane_b32 s42, v251, 6
	v_readlane_b32 s43, v251, 7
	v_readlane_b32 s44, v251, 8
	v_readlane_b32 s45, v251, 9
	v_readlane_b32 s46, v251, 10
	v_readlane_b32 s47, v251, 11
	v_readlane_b32 s48, v251, 12
	v_readlane_b32 s49, v251, 13
	v_readlane_b32 s50, v251, 14
	v_readlane_b32 s51, v251, 15
	s_cbranch_vccnz .LBB0_1245
	s_waitcnt vmcnt(8)
	v_mov_b64_e32 v[114:115], v[214:215]
	v_mov_b64_e32 v[116:117], v[216:217]
	v_mov_b64_e32 v[118:119], v[218:219]
	v_mov_b64_e32 v[120:121], v[220:221]

.LBB0_1248:
	v_mov_b64_e32 v[122:123], v[222:223]
	v_mov_b64_e32 v[124:125], v[224:225]
	v_mov_b64_e32 v[126:127], v[226:227]
	v_mov_b64_e32 v[128:129], v[228:229]
	s_mov_b32 s98, 0x70000
	s_mov_b32 s99, 0
	v_lshl_add_u64 v[246:247], v[142:143], 0, s[98:99]
	global_load_dwordx4 v[214:217], v[246:247], off
	global_load_dwordx4 v[218:221], v[246:247], off offset:16
	global_load_dwordx4 v[222:225], v[246:247], off offset:512
	global_load_dwordx4 v[226:229], v[246:247], off offset:528

.Lopw_1:
	v_pk_add_f32 v[140:141], v[112:113], v[116:117]
	v_pk_add_f32 v[142:143], v[110:111], v[114:115]
	v_pk_add_f32 v[114:115], v[104:105], v[124:125]
	v_pk_add_f32 v[116:117], v[102:103], v[122:123]
	v_pk_add_f32 v[144:145], v[108:109], v[120:121]
	v_pk_add_f32 v[156:157], v[106:107], v[118:119]
	v_mul_f32_e32 v106, v143, v143
	v_mul_f32_e32 v107, v141, v141
	v_pk_add_f32 v[120:121], v[98:99], v[126:127]
	v_mul_f32_e32 v98, v117, v117
	v_mul_f32_e32 v99, v115, v115
	v_fmac_f32_e32 v106, v142, v142
	v_fmac_f32_e32 v107, v140, v140
	v_fmac_f32_e32 v98, v116, v116
	v_fmac_f32_e32 v99, v114, v114
	v_add_f32_e32 v106, v106, v107
	v_mul_f32_e32 v107, v157, v157
	v_add_f32_e32 v98, v98, v99
	v_mul_f32_e32 v99, v121, v121
	v_fmac_f32_e32 v107, v156, v156
	v_pk_add_f32 v[118:119], v[100:101], v[128:129]
	v_fmac_f32_e32 v99, v120, v120
	v_add_f32_e32 v106, v107, v106
	v_mul_f32_e32 v107, v145, v145
	v_add_f32_e32 v98, v99, v98
	v_mul_f32_e32 v99, v119, v119
	v_fmac_f32_e32 v107, v144, v144
	v_fmac_f32_e32 v99, v118, v118
	v_add_f32_e32 v106, v107, v106
	v_add_f32_e32 v98, v99, v98
	v_add_f32_e32 v98, v106, v98
	ds_bpermute_b32 v99, v178, v98
	s_waitcnt lgkmcnt(0)
	v_add_f32_e32 v98, v98, v99
	ds_bpermute_b32 v99, v179, v98
	s_and_saveexec_b64 s[12:13], s[4:5]
	s_cbranch_execz .LBB0_1251
	s_waitcnt lgkmcnt(0)
	v_add_f32_e32 v98, v98, v99
	v_lshl_add_u32 v99, v175, 4, s14
	ds_write_b32 v99, v98

.LBB0_1253:
	v_readlane_b32 s36, v251, 0
	v_readlane_b32 s37, v251, 1
	s_andn2_b64 vcc, exec, s[12:13]
	v_readlane_b32 s38, v251, 2
	v_lshl_add_u64 v[126:127], v[106:107], 2, s[36:37]
	v_readlane_b32 s39, v251, 3
	v_readlane_b32 s40, v251, 4
	v_readlane_b32 s41, v251, 5
	v_readlane_b32 s42, v251, 6
	v_readlane_b32 s43, v251, 7
	v_readlane_b32 s44, v251, 8
	v_readlane_b32 s45, v251, 9
	v_readlane_b32 s46, v251, 10
	v_readlane_b32 s47, v251, 11
	v_readlane_b32 s48, v251, 12
	v_readlane_b32 s49, v251, 13
	v_readlane_b32 s50, v251, 14
	v_readlane_b32 s51, v251, 15
	s_cbranch_vccnz .LBB0_1255
	s_waitcnt vmcnt(8)
	v_mov_b64_e32 v[98:99], v[230:231]
	v_mov_b64_e32 v[100:101], v[232:233]
	v_mov_b64_e32 v[102:103], v[234:235]
	v_mov_b64_e32 v[104:105], v[236:237]

.LBB0_1258:
	v_mov_b64_e32 v[106:107], v[238:239]
	v_mov_b64_e32 v[108:109], v[240:241]
	v_mov_b64_e32 v[110:111], v[242:243]
	v_mov_b64_e32 v[112:113], v[244:245]
	s_mov_b32 s98, 0x70000
	s_mov_b32 s99, 0
	v_lshl_add_u64 v[246:247], v[126:127], 0, s[98:99]
	global_load_dwordx4 v[230:233], v[246:247], off
	global_load_dwordx4 v[234:237], v[246:247], off offset:16
	global_load_dwordx4 v[238:241], v[246:247], off offset:512
	global_load_dwordx4 v[242:245], v[246:247], off offset:528

.Lopw_2:
	v_pk_add_f32 v[124:125], v[96:97], v[100:101]
	v_pk_add_f32 v[126:127], v[94:95], v[98:99]
	v_pk_add_f32 v[98:99], v[88:89], v[108:109]
	v_pk_add_f32 v[100:101], v[86:87], v[106:107]
	v_pk_add_f32 v[128:129], v[92:93], v[104:105]
	v_pk_add_f32 v[158:159], v[90:91], v[102:103]
	v_mul_f32_e32 v90, v127, v127
	v_mul_f32_e32 v91, v125, v125
	v_pk_add_f32 v[104:105], v[82:83], v[110:111]
	v_mul_f32_e32 v82, v101, v101
	v_mul_f32_e32 v83, v99, v99
	v_fmac_f32_e32 v90, v126, v126
	v_fmac_f32_e32 v91, v124, v124
	v_fmac_f32_e32 v82, v100, v100
	v_fmac_f32_e32 v83, v98, v98
	v_add_f32_e32 v90, v90, v91
	v_mul_f32_e32 v91, v159, v159
	v_add_f32_e32 v82, v82, v83
	v_mul_f32_e32 v83, v105, v105
	v_fmac_f32_e32 v91, v158, v158
	v_pk_add_f32 v[102:103], v[84:85], v[112:113]
	v_fmac_f32_e32 v83, v104, v104
	v_add_f32_e32 v90, v91, v90
	v_mul_f32_e32 v91, v129, v129
	v_add_f32_e32 v82, v83, v82
	v_mul_f32_e32 v83, v103, v103
	v_fmac_f32_e32 v91, v128, v128
	v_fmac_f32_e32 v83, v102, v102
	v_add_f32_e32 v90, v91, v90
	v_add_f32_e32 v82, v83, v82
	v_add_f32_e32 v82, v90, v82
	ds_bpermute_b32 v83, v178, v82
	s_waitcnt lgkmcnt(0)
	v_add_f32_e32 v82, v82, v83
	ds_bpermute_b32 v83, v179, v82
	s_and_saveexec_b64 s[12:13], s[4:5]
	s_cbranch_execz .LBB0_1261
	s_waitcnt lgkmcnt(0)
	v_add_f32_e32 v82, v82, v83
	v_lshl_add_u32 v83, v176, 4, s14
	ds_write_b32 v83, v82

.LBB0_1263:
	v_readlane_b32 s36, v251, 0
	v_readlane_b32 s37, v251, 1
	s_andn2_b64 vcc, exec, s[12:13]
	v_readlane_b32 s38, v251, 2
	v_lshl_add_u64 v[110:111], v[90:91], 2, s[36:37]
	v_readlane_b32 s39, v251, 3
	v_readlane_b32 s40, v251, 4
	v_readlane_b32 s41, v251, 5
	v_readlane_b32 s42, v251, 6
	v_readlane_b32 s43, v251, 7
	v_readlane_b32 s44, v251, 8
	v_readlane_b32 s45, v251, 9
	v_readlane_b32 s46, v251, 10
	v_readlane_b32 s47, v251, 11
	v_readlane_b32 s48, v251, 12
	v_readlane_b32 s49, v251, 13
	v_readlane_b32 s50, v251, 14
	v_readlane_b32 s51, v251, 15
	s_cbranch_vccnz .LBB0_1265
	s_waitcnt vmcnt(8)
	v_mov_b64_e32 v[82:83], v[198:199]
	v_mov_b64_e32 v[84:85], v[200:201]
	v_mov_b64_e32 v[86:87], v[202:203]
	v_mov_b64_e32 v[88:89], v[204:205]

.LBB0_1268:
	v_mov_b64_e32 v[90:91], v[206:207]
	v_mov_b64_e32 v[92:93], v[208:209]
	v_mov_b64_e32 v[94:95], v[210:211]
	v_mov_b64_e32 v[96:97], v[212:213]
	s_mov_b32 s98, 0x70000
	s_mov_b32 s99, 0
	v_lshl_add_u64 v[246:247], v[110:111], 0, s[98:99]
	global_load_dwordx4 v[198:201], v[246:247], off
	global_load_dwordx4 v[202:205], v[246:247], off offset:16
	global_load_dwordx4 v[206:209], v[246:247], off offset:512
	global_load_dwordx4 v[210:213], v[246:247], off offset:528

.Lopw_3:
	v_pk_add_f32 v[108:109], v[80:81], v[84:85]
	v_pk_add_f32 v[110:111], v[78:79], v[82:83]
	v_pk_add_f32 v[82:83], v[72:73], v[92:93]
	v_pk_add_f32 v[84:85], v[70:71], v[90:91]
	v_pk_add_f32 v[112:113], v[76:77], v[88:89]
	v_pk_add_f32 v[160:161], v[74:75], v[86:87]
	v_mul_f32_e32 v74, v111, v111
	v_mul_f32_e32 v75, v109, v109
	v_pk_add_f32 v[88:89], v[66:67], v[94:95]
	v_mul_f32_e32 v66, v85, v85
	v_mul_f32_e32 v67, v83, v83
	v_fmac_f32_e32 v74, v110, v110
	v_fmac_f32_e32 v75, v108, v108
	v_fmac_f32_e32 v66, v84, v84
	v_fmac_f32_e32 v67, v82, v82
	v_add_f32_e32 v74, v74, v75
	v_mul_f32_e32 v75, v161, v161
	v_add_f32_e32 v66, v66, v67
	v_mul_f32_e32 v67, v89, v89
	v_fmac_f32_e32 v75, v160, v160
	v_pk_add_f32 v[86:87], v[68:69], v[96:97]
	v_fmac_f32_e32 v67, v88, v88
	v_add_f32_e32 v74, v75, v74
	v_mul_f32_e32 v75, v113, v113
	v_add_f32_e32 v66, v67, v66
	v_mul_f32_e32 v67, v87, v87
	v_fmac_f32_e32 v75, v112, v112
	v_fmac_f32_e32 v67, v86, v86
	v_add_f32_e32 v74, v75, v74
	v_add_f32_e32 v66, v67, v66
	v_add_f32_e32 v66, v74, v66
	ds_bpermute_b32 v67, v178, v66
	s_waitcnt lgkmcnt(0)
	v_add_f32_e32 v66, v66, v67
	ds_bpermute_b32 v67, v179, v66
	s_and_saveexec_b64 s[12:13], s[4:5]
	s_cbranch_execz .LBB0_1271
	s_waitcnt lgkmcnt(0)
	v_add_f32_e32 v66, v66, v67
	v_lshl_add_u32 v67, v177, 4, s14
	ds_write_b32 v67, v66

.LBB0_1273:
	v_readlane_b32 s36, v251, 0
	v_readlane_b32 s37, v251, 1
	s_andn2_b64 vcc, exec, s[12:13]
	v_readlane_b32 s38, v251, 2
	v_lshl_add_u64 v[94:95], v[74:75], 2, s[36:37]
	v_readlane_b32 s39, v251, 3
	v_readlane_b32 s40, v251, 4
	v_readlane_b32 s41, v251, 5
	v_readlane_b32 s42, v251, 6
	v_readlane_b32 s43, v251, 7
	v_readlane_b32 s44, v251, 8
	v_readlane_b32 s45, v251, 9
	v_readlane_b32 s46, v251, 10
	v_readlane_b32 s47, v251, 11
	v_readlane_b32 s48, v251, 12
	v_readlane_b32 s49, v251, 13
	v_readlane_b32 s50, v251, 14
	v_readlane_b32 s51, v251, 15
	s_cbranch_vccnz .LBB0_1275
	s_waitcnt vmcnt(8)
	v_mov_b64_e32 v[66:67], v[214:215]
	v_mov_b64_e32 v[68:69], v[216:217]
	v_mov_b64_e32 v[70:71], v[218:219]
	v_mov_b64_e32 v[72:73], v[220:221]

.LBB0_1278:
	v_mov_b64_e32 v[74:75], v[222:223]
	v_mov_b64_e32 v[76:77], v[224:225]
	v_mov_b64_e32 v[78:79], v[226:227]
	v_mov_b64_e32 v[80:81], v[228:229]
	s_mov_b32 s98, 0x30000
	s_mov_b32 s99, 0
	v_lshl_add_u64 v[246:247], v[94:95], 0, s[98:99]
	global_load_dwordx4 v[214:217], v[246:247], off
	global_load_dwordx4 v[218:221], v[246:247], off offset:16
	global_load_dwordx4 v[222:225], v[246:247], off offset:512
	global_load_dwordx4 v[226:229], v[246:247], off offset:528

.Lopw_4:
	v_pk_add_f32 v[92:93], v[64:65], v[68:69]
	v_pk_add_f32 v[94:95], v[62:63], v[66:67]
	v_pk_add_f32 v[66:67], v[56:57], v[76:77]
	v_pk_add_f32 v[68:69], v[54:55], v[74:75]
	v_pk_add_f32 v[96:97], v[60:61], v[72:73]
	v_pk_add_f32 v[166:167], v[58:59], v[70:71]
	v_mul_f32_e32 v58, v95, v95
	v_mul_f32_e32 v59, v93, v93
	v_pk_add_f32 v[72:73], v[50:51], v[78:79]
	v_mul_f32_e32 v50, v69, v69
	v_mul_f32_e32 v51, v67, v67
	v_fmac_f32_e32 v58, v94, v94
	v_fmac_f32_e32 v59, v92, v92
	v_fmac_f32_e32 v50, v68, v68
	v_fmac_f32_e32 v51, v66, v66
	v_add_f32_e32 v58, v58, v59
	v_mul_f32_e32 v59, v167, v167
	v_add_f32_e32 v50, v50, v51
	v_mul_f32_e32 v51, v73, v73
	v_fmac_f32_e32 v59, v166, v166
	v_pk_add_f32 v[70:71], v[52:53], v[80:81]
	v_fmac_f32_e32 v51, v72, v72
	v_add_f32_e32 v58, v59, v58
	v_mul_f32_e32 v59, v97, v97
	v_add_f32_e32 v50, v51, v50
	v_mul_f32_e32 v51, v71, v71
	v_fmac_f32_e32 v59, v96, v96
	v_fmac_f32_e32 v51, v70, v70
	v_add_f32_e32 v58, v59, v58
	v_add_f32_e32 v50, v51, v50
	v_add_f32_e32 v50, v58, v50
	ds_bpermute_b32 v51, v178, v50
	s_waitcnt lgkmcnt(0)
	v_add_f32_e32 v50, v50, v51
	ds_bpermute_b32 v51, v179, v50
	s_and_saveexec_b64 s[12:13], s[4:5]
	s_cbranch_execz .LBB0_1281
	s_waitcnt lgkmcnt(0)
	v_add_f32_e32 v50, v50, v51
	v_lshl_add_u32 v51, v168, 4, s14
	ds_write_b32 v51, v50

.LBB0_1283:
	v_readlane_b32 s36, v251, 0
	v_readlane_b32 s37, v251, 1
	s_andn2_b64 vcc, exec, s[12:13]
	v_readlane_b32 s38, v251, 2
	v_lshl_add_u64 v[78:79], v[58:59], 2, s[36:37]
	v_readlane_b32 s39, v251, 3
	v_readlane_b32 s40, v251, 4
	v_readlane_b32 s41, v251, 5
	v_readlane_b32 s42, v251, 6
	v_readlane_b32 s43, v251, 7
	v_readlane_b32 s44, v251, 8
	v_readlane_b32 s45, v251, 9
	v_readlane_b32 s46, v251, 10
	v_readlane_b32 s47, v251, 11
	v_readlane_b32 s48, v251, 12
	v_readlane_b32 s49, v251, 13
	v_readlane_b32 s50, v251, 14
	v_readlane_b32 s51, v251, 15
	s_cbranch_vccnz .LBB0_1285
	s_waitcnt vmcnt(8)
	v_mov_b64_e32 v[50:51], v[230:231]
	v_mov_b64_e32 v[52:53], v[232:233]
	v_mov_b64_e32 v[54:55], v[234:235]
	v_mov_b64_e32 v[56:57], v[236:237]

.LBB0_1288:
	v_mov_b64_e32 v[58:59], v[238:239]
	v_mov_b64_e32 v[60:61], v[240:241]
	v_mov_b64_e32 v[62:63], v[242:243]
	v_mov_b64_e32 v[64:65], v[244:245]

.Lopw_5:
	v_pk_add_f32 v[76:77], v[48:49], v[52:53]
	v_pk_add_f32 v[78:79], v[46:47], v[50:51]
	v_pk_add_f32 v[50:51], v[40:41], v[60:61]
	v_pk_add_f32 v[52:53], v[38:39], v[58:59]
	v_pk_add_f32 v[80:81], v[44:45], v[56:57]
	v_pk_add_f32 v[168:169], v[42:43], v[54:55]
	v_mul_f32_e32 v42, v79, v79
	v_mul_f32_e32 v43, v77, v77
	v_pk_add_f32 v[56:57], v[34:35], v[62:63]
	v_mul_f32_e32 v34, v53, v53
	v_mul_f32_e32 v35, v51, v51
	v_fmac_f32_e32 v42, v78, v78
	v_fmac_f32_e32 v43, v76, v76
	v_fmac_f32_e32 v34, v52, v52
	v_fmac_f32_e32 v35, v50, v50
	v_add_f32_e32 v42, v42, v43
	v_mul_f32_e32 v43, v169, v169
	v_add_f32_e32 v34, v34, v35
	v_mul_f32_e32 v35, v57, v57
	v_fmac_f32_e32 v43, v168, v168
	v_pk_add_f32 v[54:55], v[36:37], v[64:65]
	v_fmac_f32_e32 v35, v56, v56
	v_add_f32_e32 v42, v43, v42
	v_mul_f32_e32 v43, v81, v81
	v_add_f32_e32 v34, v35, v34
	v_mul_f32_e32 v35, v55, v55
	v_fmac_f32_e32 v43, v80, v80
	v_fmac_f32_e32 v35, v54, v54
	v_add_f32_e32 v42, v43, v42
	v_add_f32_e32 v34, v35, v34
	v_add_f32_e32 v34, v42, v34
	ds_bpermute_b32 v35, v178, v34
	s_waitcnt lgkmcnt(0)
	v_add_f32_e32 v34, v34, v35
	ds_bpermute_b32 v35, v179, v34
	s_and_saveexec_b64 s[12:13], s[4:5]
	s_cbranch_execz .LBB0_1291
	s_waitcnt lgkmcnt(0)
	v_add_f32_e32 v34, v34, v35
	v_lshl_add_u32 v35, v170, 4, s14
	ds_write_b32 v35, v34

.LBB0_1293:
	v_readlane_b32 s36, v251, 0
	v_readlane_b32 s37, v251, 1
	s_andn2_b64 vcc, exec, s[12:13]
	v_readlane_b32 s38, v251, 2
	v_lshl_add_u64 v[62:63], v[42:43], 2, s[36:37]
	v_readlane_b32 s39, v251, 3
	v_readlane_b32 s40, v251, 4
	v_readlane_b32 s41, v251, 5
	v_readlane_b32 s42, v251, 6
	v_readlane_b32 s43, v251, 7
	v_readlane_b32 s44, v251, 8
	v_readlane_b32 s45, v251, 9
	v_readlane_b32 s46, v251, 10
	v_readlane_b32 s47, v251, 11
	v_readlane_b32 s48, v251, 12
	v_readlane_b32 s49, v251, 13
	v_readlane_b32 s50, v251, 14
	v_readlane_b32 s51, v251, 15
	s_cbranch_vccnz .LBB0_1295
	s_waitcnt vmcnt(4)
	v_mov_b64_e32 v[34:35], v[198:199]
	v_mov_b64_e32 v[36:37], v[200:201]
	v_mov_b64_e32 v[38:39], v[202:203]
	v_mov_b64_e32 v[40:41], v[204:205]

.LBB0_1298:
	v_mov_b64_e32 v[42:43], v[206:207]
	v_mov_b64_e32 v[44:45], v[208:209]
	v_mov_b64_e32 v[46:47], v[210:211]
	v_mov_b64_e32 v[48:49], v[212:213]

.Lopw_6:
	v_pk_add_f32 v[60:61], v[32:33], v[36:37]
	v_pk_add_f32 v[62:63], v[30:31], v[34:35]
	v_pk_add_f32 v[34:35], v[24:25], v[44:45]
	v_pk_add_f32 v[36:37], v[22:23], v[42:43]
	v_pk_add_f32 v[64:65], v[28:29], v[40:41]
	v_pk_add_f32 v[170:171], v[26:27], v[38:39]
	v_mul_f32_e32 v26, v63, v63
	v_mul_f32_e32 v27, v61, v61
	v_pk_add_f32 v[40:41], v[18:19], v[46:47]
	v_mul_f32_e32 v18, v37, v37
	v_mul_f32_e32 v19, v35, v35
	v_fmac_f32_e32 v26, v62, v62
	v_fmac_f32_e32 v27, v60, v60
	v_fmac_f32_e32 v18, v36, v36
	v_fmac_f32_e32 v19, v34, v34
	v_add_f32_e32 v26, v26, v27
	v_mul_f32_e32 v27, v171, v171
	v_add_f32_e32 v18, v18, v19
	v_mul_f32_e32 v19, v41, v41
	v_fmac_f32_e32 v27, v170, v170
	v_pk_add_f32 v[38:39], v[20:21], v[48:49]
	v_fmac_f32_e32 v19, v40, v40
	v_add_f32_e32 v26, v27, v26
	v_mul_f32_e32 v27, v65, v65
	v_add_f32_e32 v18, v19, v18
	v_mul_f32_e32 v19, v39, v39
	v_fmac_f32_e32 v27, v64, v64
	v_fmac_f32_e32 v19, v38, v38
	v_add_f32_e32 v26, v27, v26
	v_add_f32_e32 v18, v19, v18
	v_add_f32_e32 v18, v26, v18
	ds_bpermute_b32 v19, v178, v18
	s_waitcnt lgkmcnt(0)
	v_add_f32_e32 v18, v18, v19
	ds_bpermute_b32 v19, v179, v18
	s_and_saveexec_b64 s[12:13], s[4:5]
	s_cbranch_execz .LBB0_1301
	s_waitcnt lgkmcnt(0)
	v_add_f32_e32 v18, v18, v19
	v_lshl_add_u32 v19, v180, 4, s14
	ds_write_b32 v19, v18

.LBB0_1303:
	v_readlane_b32 s36, v251, 0
	v_readlane_b32 s37, v251, 1
	s_andn2_b64 vcc, exec, s[12:13]
	v_readlane_b32 s38, v251, 2
	v_lshl_add_u64 v[46:47], v[26:27], 2, s[36:37]
	v_readlane_b32 s39, v251, 3
	v_readlane_b32 s40, v251, 4
	v_readlane_b32 s41, v251, 5
	v_readlane_b32 s42, v251, 6
	v_readlane_b32 s43, v251, 7
	v_readlane_b32 s44, v251, 8
	v_readlane_b32 s45, v251, 9
	v_readlane_b32 s46, v251, 10
	v_readlane_b32 s47, v251, 11
	v_readlane_b32 s48, v251, 12
	v_readlane_b32 s49, v251, 13
	v_readlane_b32 s50, v251, 14
	v_readlane_b32 s51, v251, 15
	s_cbranch_vccnz .LBB0_1305
	s_waitcnt vmcnt(0)
	v_mov_b64_e32 v[18:19], v[214:215]
	v_mov_b64_e32 v[20:21], v[216:217]
	v_mov_b64_e32 v[22:23], v[218:219]
	v_mov_b64_e32 v[24:25], v[220:221]

.LBB0_1308:
	v_mov_b64_e32 v[26:27], v[222:223]
	v_mov_b64_e32 v[28:29], v[224:225]
	v_mov_b64_e32 v[30:31], v[226:227]
	v_mov_b64_e32 v[32:33], v[228:229]

.Lopw_7:
	v_pk_add_f32 v[16:17], v[16:17], v[20:21]
	v_pk_add_f32 v[14:15], v[14:15], v[18:19]
	v_mul_f32_e32 v19, v17, v17
	v_mul_f32_e32 v18, v15, v15
	v_pk_add_f32 v[10:11], v[10:11], v[22:23]
	v_fmac_f32_e32 v18, v14, v14
	v_fmac_f32_e32 v19, v16, v16
	v_add_f32_e32 v18, v18, v19
	v_mul_f32_e32 v19, v11, v11
	v_pk_add_f32 v[12:13], v[12:13], v[24:25]
	v_fmac_f32_e32 v19, v10, v10
	v_add_f32_e32 v18, v19, v18
	v_mul_f32_e32 v19, v13, v13
	v_fmac_f32_e32 v19, v12, v12
	v_pk_add_f32 v[8:9], v[8:9], v[28:29]
	v_pk_add_f32 v[6:7], v[6:7], v[26:27]
	v_add_f32_e32 v18, v19, v18
	v_mul_f32_e32 v19, v7, v7
	v_mul_f32_e32 v20, v9, v9
	v_pk_add_f32 v[2:3], v[2:3], v[30:31]
	v_fmac_f32_e32 v19, v6, v6
	v_fmac_f32_e32 v20, v8, v8
	v_add_f32_e32 v19, v19, v20
	v_mul_f32_e32 v20, v3, v3
	v_pk_add_f32 v[4:5], v[4:5], v[32:33]
	v_fmac_f32_e32 v20, v2, v2
	v_add_f32_e32 v19, v20, v19
	v_mul_f32_e32 v20, v5, v5
	v_fmac_f32_e32 v20, v4, v4
	v_add_f32_e32 v19, v20, v19
	v_add_f32_e32 v18, v18, v19
	ds_bpermute_b32 v19, v178, v18
	s_waitcnt lgkmcnt(0)
	v_add_f32_e32 v18, v18, v19
	ds_bpermute_b32 v19, v179, v18
	s_and_saveexec_b64 s[12:13], s[4:5]
	s_cbranch_execz .LBB0_1311
	s_waitcnt lgkmcnt(0)
	v_add_f32_e32 v18, v18, v19
	v_lshl_add_u32 v19, v48, 4, s14
	ds_write_b32 v19, v18
